# group start stagger s_sleep 20 per index step
# baseline (speedup 1.0000x reference)
; __device__ __forceinline__ void mk_p3(const Ptrs& P, LAS unsigned char* lds, int tid, int wave, int lane, int bx, int G, bool dry) {
;     ...
;         { bool pre = false; for (int u = bx; u < NB * 32 * 4; u += G) pre = attn_unit(P, lds, u, tid, wave, lane, pre, u + G < NB * 32 * 4 ? u + G : -1); }
.Lstg_loop:
	s_cmp_eq_u32 vcc_lo, 0
	s_cbranch_scc1 .Lstg_done
	s_sleep 20
	s_sub_u32 vcc_lo, vcc_lo, 1
	s_branch .Lstg_loop
